# speedup vs baseline: 1.0060x; 1.0060x over previous
; #define MFMA16(a, b, c) __builtin_amdgcn_mfma_f32_16x16x32_bf16((a), (b), (c), 0, 0, 0)
; static __device__ __forceinline__ void attn_item(const Params& p, int head, int j, char* smraw) {
;     ...
;     bf16x8 pf[2][2];
; #pragma unroll
;     for (int qt = 0; qt < 2; ++qt) {
;       float ps = 0.f;
; #pragma unroll
;       for (int kt = 0; kt < 4; ++kt)
; #pragma unroll
;         for (int r = 0; r < 4; ++r) {
;           const float pv = __builtin_amdgcn_exp2f(sacc[kt][qt][r]);
;           sacc[kt][qt][r] = pv; ps += pv;
;         }
;       lrun[qt] += ps;
; #pragma unroll
;       for (int k2 = 0; k2 < 2; ++k2) {
;         u32x4 pk = {cvtpk(sacc[2 * k2][qt][0], sacc[2 * k2][qt][1]), cvtpk(sacc[2 * k2][qt][2], sacc[2 * k2][qt][3]),
;                     cvtpk(sacc[2 * k2 + 1][qt][0], sacc[2 * k2 + 1][qt][1]), cvtpk(sacc[2 * k2 + 1][qt][2], sacc[2 * k2 + 1][qt][3])};
;         pf[qt][k2] = *(bf16x8*)&pk;
;       }
;     }
;     {
;       bf16x8 vf[2][4];
; #pragma unroll
;       for (int k2 = 0; k2 < 2; ++k2)
; #pragma unroll
;         for (int dt = 0; dt < 4; ++dt) vf[k2][dt] = *(const bf16x8*)(cV + (dt * 16 + l15) * 64 + (((k2 * 4 + quad) ^ (l15 & 7)) << 3));
;       __builtin_amdgcn_sched_barrier(0);
;       __builtin_amdgcn_s_setprio(1);
; #pragma unroll
;       for (int k2 = 0; k2 < 2; ++k2)
; #pragma unroll
;         for (int dt = 0; dt < 4; ++dt)
; #pragma unroll
;           for (int qt = 0; qt < 2; ++qt) oacc[dt][qt] = MFMA16(vf[k2][dt], pf[qt][k2], oacc[dt][qt]);
;       __builtin_amdgcn_s_setprio(0);
;       __builtin_amdgcn_sched_barrier(0);
;     }
;     ...
;     ATT_STORE(rkB, rvB, 1);
;     __syncthreads();
;     if (t + 3 < NT) ATT_LOAD(rkB, rvB, t + 3);
.LBB0_380:
	v_exp_f32_e32 v173, v124
	v_exp_f32_e32 v169, v126
	v_exp_f32_e32 v161, v122
	v_exp_f32_e32 v172, v108
	v_exp_f32_e32 v170, v109
	v_exp_f32_e32 v168, v110
	v_exp_f32_e32 v166, v111
	v_exp_f32_e32 v164, v104
	v_exp_f32_e32 v162, v105
	v_exp_f32_e32 v160, v106
	v_exp_f32_e32 v158, v107
	v_exp_f32_e32 v156, v100
	v_exp_f32_e32 v126, v101
	v_exp_f32_e32 v124, v102
	v_exp_f32_e32 v122, v103
	ds_read_b128 v[100:103], v187 offset:16384
	ds_read_b128 v[104:107], v187 offset:18432
	ds_read_b128 v[108:111], v187 offset:20480
	ds_read_b128 v[200:203], v187 offset:22528
	ds_read_b128 v[204:207], v188 offset:16384
	ds_read_b128 v[208:211], v188 offset:18432
	ds_read_b128 v[212:215], v188 offset:20480
	ds_read_b128 v[216:219], v188 offset:22528
	v_exp_f32_e32 v171, v125
	v_exp_f32_e32 v167, v127
	v_exp_f32_e32 v165, v120
	v_exp_f32_e32 v163, v121
	v_exp_f32_e32 v159, v123
	v_cvt_pk_bf16_f32 v228, v172, v170
	v_cvt_pk_bf16_f32 v229, v168, v166
	v_cvt_pk_bf16_f32 v230, v164, v162
	v_cvt_pk_bf16_f32 v231, v160, v158
	v_cvt_pk_bf16_f32 v192, v173, v171
	v_cvt_pk_bf16_f32 v193, v169, v167
	v_cvt_pk_bf16_f32 v194, v165, v163
	v_cvt_pk_bf16_f32 v195, v161, v159
	s_setprio 1
	s_nop 1
	s_waitcnt lgkmcnt(7)
	v_mfma_f32_16x16x32_bf16 v[92:95], v[100:103], v[192:195], v[92:95]
	v_mfma_f32_16x16x32_bf16 v[76:79], v[100:103], v[228:231], v[76:79]
	v_exp_f32_e32 v157, v116
	v_exp_f32_e32 v127, v117
	s_waitcnt lgkmcnt(6)
	v_mfma_f32_16x16x32_bf16 v[100:103], v[104:107], v[192:195], v[88:91]
	v_exp_f32_e32 v125, v118
	v_exp_f32_e32 v123, v119
	v_mfma_f32_16x16x32_bf16 v[72:75], v[104:107], v[228:231], v[72:75]
	v_exp_f32_e32 v121, v112
	v_exp_f32_e32 v119, v113
	s_waitcnt lgkmcnt(5)
	v_mfma_f32_16x16x32_bf16 v[104:107], v[108:111], v[192:195], v[84:87]
	v_exp_f32_e32 v117, v114
	v_exp_f32_e32 v113, v115
	v_mfma_f32_16x16x32_bf16 v[68:71], v[108:111], v[228:231], v[68:71]
	v_exp_f32_e32 v120, v96
	v_exp_f32_e32 v118, v97
	s_waitcnt lgkmcnt(4)
	v_mfma_f32_16x16x32_bf16 v[108:111], v[200:203], v[192:195], v[80:83]
	v_exp_f32_e32 v116, v98
	v_exp_f32_e32 v112, v99
	v_cvt_pk_bf16_f32 v196, v157, v127
	v_cvt_pk_bf16_f32 v197, v125, v123
	v_mfma_f32_16x16x32_bf16 v[64:67], v[200:203], v[228:231], v[64:67]
	v_cvt_pk_bf16_f32 v198, v121, v119
	v_cvt_pk_bf16_f32 v199, v117, v113
	v_cvt_pk_bf16_f32 v220, v156, v126
	v_cvt_pk_bf16_f32 v221, v124, v122
	v_cvt_pk_bf16_f32 v222, v120, v118
	v_cvt_pk_bf16_f32 v223, v116, v112
	v_add_f32_e32 v226, v170, v172
	v_add_f32_e32 v227, v171, v173
	s_waitcnt lgkmcnt(3)
	v_mfma_f32_16x16x32_bf16 v[92:95], v[204:207], v[196:199], v[92:95]
	v_add_f32_e32 v226, v168, v226
	v_add_f32_e32 v227, v169, v227
	v_add_f32_e32 v226, v166, v226
	v_add_f32_e32 v227, v167, v227
	v_mfma_f32_16x16x32_bf16 v[88:91], v[204:207], v[220:223], v[76:79]
	v_add_f32_e32 v226, v164, v226
	v_add_f32_e32 v227, v165, v227
	v_add_f32_e32 v226, v162, v226
	v_add_f32_e32 v227, v163, v227
	s_waitcnt lgkmcnt(2)
	v_mfma_f32_16x16x32_bf16 v[84:87], v[208:211], v[196:199], v[100:103]
	v_add_f32_e32 v226, v160, v226
	v_add_f32_e32 v227, v161, v227
	v_add_f32_e32 v226, v158, v226
	v_add_f32_e32 v227, v159, v227
	v_mfma_f32_16x16x32_bf16 v[80:83], v[208:211], v[220:223], v[72:75]
	v_add_f32_e32 v226, v156, v226
	v_add_f32_e32 v227, v157, v227
	v_add_f32_e32 v226, v126, v226
	v_add_f32_e32 v227, v127, v227
	s_waitcnt lgkmcnt(1)
	v_mfma_f32_16x16x32_bf16 v[76:79], v[212:215], v[196:199], v[104:107]
	v_add_f32_e32 v226, v124, v226
	v_add_f32_e32 v227, v125, v227
	v_add_f32_e32 v226, v122, v226
	v_add_f32_e32 v227, v123, v227
	v_mfma_f32_16x16x32_bf16 v[72:75], v[212:215], v[220:223], v[68:71]
	v_add_f32_e32 v226, v120, v226
	v_add_f32_e32 v227, v121, v227
	v_add_f32_e32 v226, v118, v226
	v_add_f32_e32 v227, v119, v227
	s_waitcnt lgkmcnt(0)
	v_mfma_f32_16x16x32_bf16 v[68:71], v[216:219], v[196:199], v[108:111]
	v_add_f32_e32 v226, v116, v226
	v_add_f32_e32 v227, v117, v227
	v_add_f32_e32 v226, v112, v226
	v_add_f32_e32 v227, v113, v227
	v_mfma_f32_16x16x32_bf16 v[64:67], v[216:219], v[220:223], v[64:67]
	s_setprio 0
	v_pk_add_f32 v[144:145], v[144:145], v[226:227]
	s_cmp_ge_u32 s3, s2
	s_waitcnt vmcnt(4)
	ds_write_b128 v179, v[44:47] offset:24576
	s_waitcnt vmcnt(3)
	ds_write_b128 v180, v[48:51] offset:24576
	s_waitcnt vmcnt(2)
	ds_write_b128 v181, v[52:55] offset:24576
	s_waitcnt vmcnt(1)
	ds_write_b128 v182, v[56:59] offset:40960
	s_waitcnt vmcnt(0)
	ds_write_b128 v183, v[60:63] offset:40960
	s_waitcnt lgkmcnt(0)
	s_barrier
	s_cbranch_scc1 .LBB0_382
	v_lshl_add_u64 v[44:45], v[142:143], 0, s[98:99]
	v_lshl_add_u64 v[48:49], v[140:141], 0, s[98:99]
	v_lshl_add_u64 v[52:53], v[138:139], 0, s[98:99]
	global_load_dwordx4 v[44:47], v[44:45], off
	s_nop 0
	global_load_dwordx4 v[48:51], v[48:49], off
	s_nop 0
	global_load_dwordx4 v[52:55], v[52:53], off
	global_load_dwordx4 v[56:59], v[134:135], off offset:384
	global_load_dwordx4 v[60:63], v[136:137], off offset:384

; #define MFMA16(a, b, c) __builtin_amdgcn_mfma_f32_16x16x32_bf16((a), (b), (c), 0, 0, 0)
; static __device__ __forceinline__ void attn_item(const Params& p, int head, int j, char* smraw) {
;     ...
;     bf16x8 pf[2][2];
; #pragma unroll
;     for (int qt = 0; qt < 2; ++qt) {
;       float ps = 0.f;
; #pragma unroll
;       for (int kt = 0; kt < 4; ++kt)
; #pragma unroll
;         for (int r = 0; r < 4; ++r) {
;           const float pv = __builtin_amdgcn_exp2f(sacc[kt][qt][r]);
;           sacc[kt][qt][r] = pv; ps += pv;
;         }
;       lrun[qt] += ps;
; #pragma unroll
;       for (int k2 = 0; k2 < 2; ++k2) {
;         u32x4 pk = {cvtpk(sacc[2 * k2][qt][0], sacc[2 * k2][qt][1]), cvtpk(sacc[2 * k2][qt][2], sacc[2 * k2][qt][3]),
;                     cvtpk(sacc[2 * k2 + 1][qt][0], sacc[2 * k2 + 1][qt][1]), cvtpk(sacc[2 * k2 + 1][qt][2], sacc[2 * k2 + 1][qt][3])};
;         pf[qt][k2] = *(bf16x8*)&pk;
;       }
;     }
;     {
;       bf16x8 vf[2][4];
; #pragma unroll
;       for (int k2 = 0; k2 < 2; ++k2)
; #pragma unroll
;         for (int dt = 0; dt < 4; ++dt) vf[k2][dt] = *(const bf16x8*)(cV + (dt * 16 + l15) * 64 + (((k2 * 4 + quad) ^ (l15 & 7)) << 3));
;       __builtin_amdgcn_sched_barrier(0);
;       __builtin_amdgcn_s_setprio(1);
; #pragma unroll
;       for (int k2 = 0; k2 < 2; ++k2)
; #pragma unroll
;         for (int dt = 0; dt < 4; ++dt)
; #pragma unroll
;           for (int qt = 0; qt < 2; ++qt) oacc[dt][qt] = MFMA16(vf[k2][dt], pf[qt][k2], oacc[dt][qt]);
;       __builtin_amdgcn_s_setprio(0);
;       __builtin_amdgcn_sched_barrier(0);
;     }
;     ...
;     compute(sK[1], sV[1], false);
;     if (t + 2 < NT) ATT_STORE(rkA, rvA, 0);
;     __syncthreads();
.LBB0_384:
	v_exp_f32_e32 v163, v124
	v_exp_f32_e32 v159, v126
	v_exp_f32_e32 v151, v122
	v_exp_f32_e32 v162, v108
	v_exp_f32_e32 v160, v109
	v_exp_f32_e32 v158, v110
	v_exp_f32_e32 v156, v111
	v_exp_f32_e32 v154, v104
	v_exp_f32_e32 v152, v105
	v_exp_f32_e32 v150, v106
	v_exp_f32_e32 v148, v107
	v_exp_f32_e32 v146, v100
	v_exp_f32_e32 v126, v101
	v_exp_f32_e32 v124, v102
	v_exp_f32_e32 v122, v103
	ds_read_b128 v[100:103], v187 offset:40960
	ds_read_b128 v[104:107], v187 offset:43008
	ds_read_b128 v[108:111], v187 offset:45056
	ds_read_b128 v[192:195], v187 offset:47104
	ds_read_b128 v[196:199], v188 offset:40960
	ds_read_b128 v[200:203], v188 offset:43008
	ds_read_b128 v[204:207], v188 offset:45056
	ds_read_b128 v[208:211], v188 offset:47104
	v_exp_f32_e32 v161, v125
	v_exp_f32_e32 v157, v127
	v_exp_f32_e32 v155, v120
	v_exp_f32_e32 v153, v121
	v_exp_f32_e32 v149, v123
	v_cvt_pk_bf16_f32 v228, v162, v160
	v_cvt_pk_bf16_f32 v229, v158, v156
	v_cvt_pk_bf16_f32 v230, v154, v152
	v_cvt_pk_bf16_f32 v231, v150, v148
	v_cvt_pk_bf16_f32 v164, v163, v161
	v_cvt_pk_bf16_f32 v165, v159, v157
	v_cvt_pk_bf16_f32 v166, v155, v153
	v_cvt_pk_bf16_f32 v167, v151, v149
	s_setprio 1
	s_nop 1
	s_waitcnt lgkmcnt(7)
	v_mfma_f32_16x16x32_bf16 v[92:95], v[100:103], v[164:167], v[92:95]
	v_mfma_f32_16x16x32_bf16 v[88:91], v[100:103], v[228:231], v[88:91]
	v_exp_f32_e32 v147, v116
	v_exp_f32_e32 v127, v117
	s_waitcnt lgkmcnt(6)
	v_mfma_f32_16x16x32_bf16 v[84:87], v[104:107], v[164:167], v[84:87]
	v_exp_f32_e32 v125, v118
	v_exp_f32_e32 v123, v119
	v_mfma_f32_16x16x32_bf16 v[80:83], v[104:107], v[228:231], v[80:83]
	v_exp_f32_e32 v121, v112
	v_exp_f32_e32 v119, v113
	s_waitcnt lgkmcnt(5)
	v_mfma_f32_16x16x32_bf16 v[100:103], v[108:111], v[164:167], v[76:79]
	v_exp_f32_e32 v117, v114
	v_exp_f32_e32 v113, v115
	v_mfma_f32_16x16x32_bf16 v[104:107], v[108:111], v[228:231], v[72:75]
	v_exp_f32_e32 v120, v96
	v_exp_f32_e32 v118, v97
	s_waitcnt lgkmcnt(4)
	v_mfma_f32_16x16x32_bf16 v[108:111], v[192:195], v[164:167], v[68:71]
	v_exp_f32_e32 v116, v98
	v_exp_f32_e32 v112, v99
	v_cvt_pk_bf16_f32 v168, v147, v127
	v_cvt_pk_bf16_f32 v169, v125, v123
	v_mfma_f32_16x16x32_bf16 v[64:67], v[192:195], v[228:231], v[64:67]
	v_cvt_pk_bf16_f32 v170, v121, v119
	v_cvt_pk_bf16_f32 v171, v117, v113
	v_cvt_pk_bf16_f32 v212, v146, v126
	v_cvt_pk_bf16_f32 v213, v124, v122
	v_cvt_pk_bf16_f32 v214, v120, v118
	v_cvt_pk_bf16_f32 v215, v116, v112
	v_add_f32_e32 v226, v160, v162
	v_add_f32_e32 v227, v161, v163
	s_waitcnt lgkmcnt(3)
	v_mfma_f32_16x16x32_bf16 v[92:95], v[196:199], v[168:171], v[92:95]
	v_add_f32_e32 v226, v158, v226
	v_add_f32_e32 v227, v159, v227
	v_add_f32_e32 v226, v156, v226
	v_add_f32_e32 v227, v157, v227
	v_mfma_f32_16x16x32_bf16 v[76:79], v[196:199], v[212:215], v[88:91]
	v_add_f32_e32 v226, v154, v226
	v_add_f32_e32 v227, v155, v227
	v_add_f32_e32 v226, v152, v226
	v_add_f32_e32 v227, v153, v227
	s_waitcnt lgkmcnt(2)
	v_mfma_f32_16x16x32_bf16 v[88:91], v[200:203], v[168:171], v[84:87]
	v_add_f32_e32 v226, v150, v226
	v_add_f32_e32 v227, v151, v227
	v_add_f32_e32 v226, v148, v226
	v_add_f32_e32 v227, v149, v227
	v_mfma_f32_16x16x32_bf16 v[72:75], v[200:203], v[212:215], v[80:83]
	v_add_f32_e32 v226, v146, v226
	v_add_f32_e32 v227, v147, v227
	v_add_f32_e32 v226, v126, v226
	v_add_f32_e32 v227, v127, v227
	s_waitcnt lgkmcnt(1)
	v_mfma_f32_16x16x32_bf16 v[84:87], v[204:207], v[168:171], v[100:103]
	v_add_f32_e32 v226, v124, v226
	v_add_f32_e32 v227, v125, v227
	v_add_f32_e32 v226, v122, v226
	v_add_f32_e32 v227, v123, v227
	v_mfma_f32_16x16x32_bf16 v[68:71], v[204:207], v[212:215], v[104:107]
	v_add_f32_e32 v226, v120, v226
	v_add_f32_e32 v227, v121, v227
	v_add_f32_e32 v226, v118, v226
	v_add_f32_e32 v227, v119, v227
	s_waitcnt lgkmcnt(0)
	v_mfma_f32_16x16x32_bf16 v[80:83], v[208:211], v[168:171], v[108:111]
	v_add_f32_e32 v226, v116, v226
	v_add_f32_e32 v227, v117, v227
	v_add_f32_e32 v226, v112, v226
	v_add_f32_e32 v227, v113, v227
	v_mfma_f32_16x16x32_bf16 v[64:67], v[208:211], v[212:215], v[64:67]
	s_setprio 0
	v_pk_add_f32 v[144:145], v[144:145], v[226:227]
	s_andn2_b64 vcc, exec, s[50:51]
	s_cbranch_vccnz .LBB0_375
	ds_write_b128 v179, v[24:27]
	ds_write_b128 v180, v[28:31]
	ds_write_b128 v181, v[32:35]
	ds_write_b128 v182, v[36:39] offset:16384
	ds_write_b128 v183, v[40:43] offset:16384
	s_branch .LBB0_375
